# dil band phase: L2-warming touch loads of the next item's Q and chunk-0 K/V rows issued at the current item's epilogue (2 dword loads per thread, results unused)
# baseline (speedup 1.0000x reference)
; #define LAS __attribute__((address_space(3)))
; template <int HD, int DV, int HW, int MODE> ...
;     ...
;     auto prefetch = [&](int c) {
;         const int jc = i0 - HW + CR * c;
; #pragma unroll
;         for (int i = 0; i < KLD; ++i) { const int idx = tid + 512 * i, row = idx / KCH, ch = idx % KCH, j = jc + row;
;             kreg[i] = (j >= 0 && j < L) ? *(const u32x4*)(kp + (tok0 + (size_t)r * j) * ld + ch * 8) : (u32x4){0, 0, 0, 0}; }
; #pragma unroll
;         for (int i = 0; i < VLD; ++i) { const int idx = tid + 512 * i, row = idx / VCH, ch = idx % VCH, j = jc + row;
;             vreg[i] = (j >= 0 && j < L) ? *(const u32x4*)(vp + (tok0 + (size_t)r * j) * ld + ch * 8) : (u32x4){0, 0, 0, 0}; }
; __device__ __forceinline__ void dil_attn_phase(const Params& p, int half, LAS unsigned char* lds) {
;     const bf16_t* PROJ = (const bf16_t*)(p.ws + WS_PROJ); bf16_t* OG = (bf16_t*)(p.ws + WS_OG); float* LSE = (float*)(p.ws + WS_LSE);
;     (void)half;
;     for (int it = blockIdx.x; it < 1536; it += gridDim.x) {
;         const int g = it >> 9, rem = it & 511, bl = rem >> 8, rest = rem & 255, h = rest & 7, cr = rest >> 3;
;         const int r = g == 0 ? 1 : (g == 1 ? 4 : 16), L = SEQ / r, pr = cr % r, qc = cr / r;
;         const size_t tok0 = (size_t)bl * SEQ + pr;
;         band_item<128, 128, 64, 0>(PROJ + g * 1024 + h * 128, PROJ + 3072 + g * 1024 + h * 128, PROJ + 6144 + h * 128, 8192, tok0, r, L, qc * 256, 0.f,
.LBB0_83:
	s_or_b64 exec, exec, s[40:41]
	s_add_i32 s21, s15, s50
	s_cmpk_gt_i32 s21, 0x5ff
	s_cbranch_scc1 .Ldt_skip
	s_ashr_i32 s10, s21, 9
	s_cmp_eq_u32 s10, 1
	s_cselect_b32 s25, 2, 4
	s_cselect_b32 s23, 3, 15
	s_cmpk_lt_u32 s21, 0x200
	s_cselect_b32 s25, 0, s25
	s_cselect_b32 s23, 0, s23
	s_bfe_u32 s11, s21, 0x50003
	s_lshr_b32 s29, s11, s25
	s_lshl_b32 s34, s29, 8
	s_lshr_b32 s28, s21, 3
	s_and_b32 s28, s28, s23
	s_lshl_b32 s46, s21, 5
	s_and_b32 s46, s46, 0x2000
	s_or_b32 s28, s28, s46
	s_lshr_b32 s47, 0x2000, s25
	s_and_b32 s46, s21, 7
	s_lshl_b32 s46, s46, 8
	s_lshl_b32 s10, s10, 11
	s_add_i32 s10, s10, s46
	v_lshrrev_b32_e32 v2, 1, v207
	v_add_u32_e32 v2, s34, v2
	v_lshlrev_b32_e32 v2, s25, v2
	v_add_u32_e32 v2, s28, v2
	v_and_b32_e32 v3, 1, v207
	v_lshlrev_b32_e32 v3, 7, v3
	v_lshl_add_u32 v2, v2, 14, v3
	v_add_u32_e32 v2, s10, v2
	global_load_dword v204, v2, s[84:85]
	v_bfe_u32 v4, v207, 1, 7
	v_add_u32_e32 v4, s34, v4
	v_subrev_u32_e32 v4, 64, v4
	v_cmp_gt_u32_e32 vcc, s47, v4
	v_mov_b32_e32 v5, s34
	v_cndmask_b32_e32 v4, v5, v4, vcc
	v_lshlrev_b32_e32 v4, s25, v4
	v_add_u32_e32 v4, s28, v4
	v_lshl_add_u32 v4, v4, 14, v3
	s_add_i32 s10, s10, 0x1800
	s_add_i32 s46, s46, 0x3000
	v_mov_b32_e32 v5, s46
	v_mov_b32_e32 v2, s10
	v_cmp_gt_u32_e32 vcc, 0x100, v207
	v_cndmask_b32_e32 v5, v5, v2, vcc
	v_add_u32_e32 v4, v5, v4
	global_load_dword v204, v4, s[84:85]
.Ldt_skip:
	v_div_scale_f32 v2, s[4:5], v1, v1, 1.0
	v_rcp_f32_e32 v3, v2
	v_div_scale_f32 v4, vcc, 1.0, v1, 1.0
	s_lshl_b64 s[4:5], s[26:27], 25
	v_fma_f32 v5, -v2, v3, 1.0
	v_fmac_f32_e32 v3, v5, v3
	v_mul_f32_e32 v5, v4, v3
	v_fma_f32 v6, -v2, v5, v4
	v_fmac_f32_e32 v5, v6, v3
	s_add_u32 s2, s90, s4
	v_fma_f32 v2, -v2, v5, v4
	s_addc_u32 s5, s91, s5
	v_div_fmas_f32 v2, v2, v3, v5
	s_add_u32 s4, s2, s22
	v_div_fixup_f32 v2, v2, v1, 1.0
	s_addc_u32 s5, s5, 0
	v_lshlrev_b64 v[4:5], 11, v[160:161]
	v_lshl_add_u64 v[4:5], s[4:5], 0, v[4:5]
	v_mov_b32_e32 v163, v0
	v_lshl_add_u64 v[4:5], v[4:5], 0, v[162:163]
	v_bfe_u32 v136, v207, 5, 1
	v_lshlrev_b32_e32 v136, 3, v136
	v_mov_b32_e32 v137, v0
	v_lshl_add_u64 v[4:5], v[4:5], 0, v[136:137]
	v_pk_mul_f32 v[6:7], v[64:65], v[2:3] op_sel_hi:[1,0]
	v_pk_mul_f32 v[8:9], v[66:67], v[2:3] op_sel_hi:[1,0]
	v_cvt_pk_bf16_f32 v128, v6, v7
	v_cvt_pk_bf16_f32 v129, v8, v9
	v_pk_mul_f32 v[6:7], v[68:69], v[2:3] op_sel_hi:[1,0]
	v_pk_mul_f32 v[8:9], v[70:71], v[2:3] op_sel_hi:[1,0]
	v_cvt_pk_bf16_f32 v130, v6, v7
	v_cvt_pk_bf16_f32 v131, v8, v9
	s_nop 1
	v_permlane32_swap_b32_e32 v128, v130
	v_permlane32_swap_b32_e32 v129, v131
	global_store_dwordx4 v[4:5], v[128:131], off
	v_pk_mul_f32 v[6:7], v[72:73], v[2:3] op_sel_hi:[1,0]
	v_pk_mul_f32 v[8:9], v[74:75], v[2:3] op_sel_hi:[1,0]
	v_cvt_pk_bf16_f32 v132, v6, v7
	v_cvt_pk_bf16_f32 v133, v8, v9
	v_pk_mul_f32 v[6:7], v[76:77], v[2:3] op_sel_hi:[1,0]
	v_pk_mul_f32 v[8:9], v[78:79], v[2:3] op_sel_hi:[1,0]
	v_cvt_pk_bf16_f32 v134, v6, v7
	v_cvt_pk_bf16_f32 v135, v8, v9
	s_nop 1
	v_permlane32_swap_b32_e32 v132, v134
	v_permlane32_swap_b32_e32 v133, v135
	global_store_dwordx4 v[4:5], v[132:135], off offset:32
	v_pk_mul_f32 v[6:7], v[48:49], v[2:3] op_sel_hi:[1,0]
	v_pk_mul_f32 v[8:9], v[50:51], v[2:3] op_sel_hi:[1,0]
	v_cvt_pk_bf16_f32 v128, v6, v7
	v_cvt_pk_bf16_f32 v129, v8, v9
	v_pk_mul_f32 v[6:7], v[52:53], v[2:3] op_sel_hi:[1,0]
	v_pk_mul_f32 v[8:9], v[54:55], v[2:3] op_sel_hi:[1,0]
	v_cvt_pk_bf16_f32 v130, v6, v7
	v_cvt_pk_bf16_f32 v131, v8, v9
	s_nop 1
	v_permlane32_swap_b32_e32 v128, v130
	v_permlane32_swap_b32_e32 v129, v131
	global_store_dwordx4 v[4:5], v[128:131], off offset:64
	v_pk_mul_f32 v[6:7], v[56:57], v[2:3] op_sel_hi:[1,0]
	v_pk_mul_f32 v[8:9], v[58:59], v[2:3] op_sel_hi:[1,0]
	v_cvt_pk_bf16_f32 v132, v6, v7
	v_cvt_pk_bf16_f32 v133, v8, v9
	v_pk_mul_f32 v[6:7], v[60:61], v[2:3] op_sel_hi:[1,0]
	v_pk_mul_f32 v[8:9], v[62:63], v[2:3] op_sel_hi:[1,0]
	v_cvt_pk_bf16_f32 v134, v6, v7
	v_cvt_pk_bf16_f32 v135, v8, v9
	s_nop 1
	v_permlane32_swap_b32_e32 v132, v134
	v_permlane32_swap_b32_e32 v133, v135
	global_store_dwordx4 v[4:5], v[132:135], off offset:96
	v_pk_mul_f32 v[6:7], v[32:33], v[2:3] op_sel_hi:[1,0]
	v_pk_mul_f32 v[8:9], v[34:35], v[2:3] op_sel_hi:[1,0]
	v_cvt_pk_bf16_f32 v128, v6, v7
	v_cvt_pk_bf16_f32 v129, v8, v9
	v_pk_mul_f32 v[6:7], v[36:37], v[2:3] op_sel_hi:[1,0]
	v_pk_mul_f32 v[8:9], v[38:39], v[2:3] op_sel_hi:[1,0]
	v_cvt_pk_bf16_f32 v130, v6, v7
	v_cvt_pk_bf16_f32 v131, v8, v9
	s_nop 1
	v_permlane32_swap_b32_e32 v128, v130
	v_permlane32_swap_b32_e32 v129, v131
	global_store_dwordx4 v[4:5], v[128:131], off offset:128
	v_pk_mul_f32 v[6:7], v[40:41], v[2:3] op_sel_hi:[1,0]
	v_pk_mul_f32 v[8:9], v[42:43], v[2:3] op_sel_hi:[1,0]
	v_cvt_pk_bf16_f32 v132, v6, v7
	v_cvt_pk_bf16_f32 v133, v8, v9
	v_pk_mul_f32 v[6:7], v[44:45], v[2:3] op_sel_hi:[1,0]
	v_pk_mul_f32 v[8:9], v[46:47], v[2:3] op_sel_hi:[1,0]
	v_cvt_pk_bf16_f32 v134, v6, v7
	v_cvt_pk_bf16_f32 v135, v8, v9
	s_nop 1
	v_permlane32_swap_b32_e32 v132, v134
	v_permlane32_swap_b32_e32 v133, v135
	global_store_dwordx4 v[4:5], v[132:135], off offset:160
	v_pk_mul_f32 v[6:7], v[16:17], v[2:3] op_sel_hi:[1,0]
	v_pk_mul_f32 v[8:9], v[18:19], v[2:3] op_sel_hi:[1,0]
	v_cvt_pk_bf16_f32 v128, v6, v7
	v_cvt_pk_bf16_f32 v129, v8, v9
	v_pk_mul_f32 v[6:7], v[20:21], v[2:3] op_sel_hi:[1,0]
	v_pk_mul_f32 v[8:9], v[22:23], v[2:3] op_sel_hi:[1,0]
	v_cvt_pk_bf16_f32 v130, v6, v7
	v_cvt_pk_bf16_f32 v131, v8, v9
	s_nop 1
	v_permlane32_swap_b32_e32 v128, v130
	v_permlane32_swap_b32_e32 v129, v131
	global_store_dwordx4 v[4:5], v[128:131], off offset:192
	v_pk_mul_f32 v[6:7], v[24:25], v[2:3] op_sel_hi:[1,0]
	v_pk_mul_f32 v[8:9], v[26:27], v[2:3] op_sel_hi:[1,0]
	v_cvt_pk_bf16_f32 v132, v6, v7
	v_cvt_pk_bf16_f32 v133, v8, v9
	v_pk_mul_f32 v[6:7], v[28:29], v[2:3] op_sel_hi:[1,0]
	v_pk_mul_f32 v[8:9], v[30:31], v[2:3] op_sel_hi:[1,0]
	v_cvt_pk_bf16_f32 v134, v6, v7
	v_cvt_pk_bf16_f32 v135, v8, v9
	s_nop 1
	v_permlane32_swap_b32_e32 v132, v134
	v_permlane32_swap_b32_e32 v133, v135
	global_store_dwordx4 v[4:5], v[132:135], off offset:224
	s_add_i32 s15, s15, s50
	s_cmpk_gt_i32 s15, 0x5ff
	s_barrier
	s_cbranch_scc1 .LBB0_73
